# forget-gate logit loads in fox_cum and the route key-table rows issued together instead of one round trip each
# speedup vs baseline: 1.0030x; 1.0030x over previous
; __device__ __forceinline__ u32x4 pack8(const float* f) { u32x4 o; o.x = pk2(f[0], f[1]); o.y = pk2(f[2], f[3]); o.z = pk2(f[4], f[5]); o.w = pk2(f[6], f[7]); return o; }
; __device__ __forceinline__ void phase_route(CArgs& A, int l, unsigned char* lds, int tid) {
;     ...
;     for (int i = tid; i < 2048; i += NTHREADS) { const int row = i >> 4, c8 = (i & 15) * 8; float f[8];
;         { const f32x4 a = *(const f32x4*)(k1 + row * 128 + c8), b4 = *(const f32x4*)(k1 + row * 128 + c8 + 4); f[0] = a.x; f[1] = a.y; f[2] = a.z; f[3] = a.w; f[4] = b4.x; f[5] = b4.y; f[6] = b4.z; f[7] = b4.w; }
;         *(u32x4*)(lds + row * RT_KP + c8 * 2) = pack8(f);
;         { const f32x4 a = *(const f32x4*)(k2 + row * 128 + c8), b4 = *(const f32x4*)(k2 + row * 128 + c8 + 4); f[0] = a.x; f[1] = a.y; f[2] = a.z; f[3] = a.w; f[4] = b4.x; f[5] = b4.y; f[6] = b4.z; f[7] = b4.w; }
;         *(u32x4*)(lds + 128 * RT_KP + row * RT_KP + c8 * 2) = pack8(f); }
.LBB0_127:
	v_ashrrev_i32_e32 v3, 4, v2
	v_lshlrev_b32_e32 v4, 7, v3
	v_ashrrev_i32_e32 v5, 31, v4
	v_and_b32_e32 v16, 0x78, v1
	v_lshlrev_b64 v[12:13], 2, v[4:5]
	v_lshl_add_u64 v[4:5], s[10:11], 0, v[12:13]
	v_lshlrev_b32_e32 v14, 2, v16
	v_mov_b32_e32 v15, v0
	v_lshl_add_u64 v[8:9], v[4:5], 0, v[14:15]
	global_load_dwordx4 v[4:7], v[8:9], off offset:16
	s_nop 0
	global_load_dwordx4 v[8:11], v[8:9], off
	v_lshl_add_u64 v[200:201], s[36:37], 0, v[12:13]
	v_lshl_add_u64 v[200:201], v[200:201], 0, v[14:15]
	global_load_dwordx4 v[204:207], v[200:201], off offset:16
	global_load_dwordx4 v[208:211], v[200:201], off
	v_mul_lo_u32 v3, v3, s8
	s_movk_i32 s0, 0x5ff
	v_cmp_lt_i32_e32 vcc, s0, v2
	v_add_u32_e32 v1, 0x1000, v1
	s_or_b64 s[40:41], vcc, s[40:41]
	s_waitcnt vmcnt(2)
	v_bfe_u32 v17, v8, 16, 1
	v_add3_u32 v8, v8, v17, s84
	v_bfe_u32 v17, v9, 16, 1
	v_lshrrev_b32_e32 v8, 16, v8
	v_add3_u32 v9, v9, v17, s84
	v_and_or_b32 v8, v9, s3, v8
	v_bfe_u32 v9, v10, 16, 1
	v_add3_u32 v9, v10, v9, s84
	v_bfe_u32 v10, v11, 16, 1
	v_lshrrev_b32_e32 v9, 16, v9
	v_add3_u32 v10, v11, v10, s84
	v_and_or_b32 v9, v10, s3, v9
	v_bfe_u32 v10, v4, 16, 1
	v_add3_u32 v4, v4, v10, s84
	v_bfe_u32 v10, v5, 16, 1
	v_lshrrev_b32_e32 v4, 16, v4
	v_add3_u32 v5, v5, v10, s84
	v_and_or_b32 v10, v5, s3, v4
	v_bfe_u32 v4, v6, 16, 1
	v_add3_u32 v4, v6, v4, s84
	v_bfe_u32 v5, v7, 16, 1
	v_lshrrev_b32_e32 v4, 16, v4
	v_add3_u32 v5, v7, v5, s84
	v_and_or_b32 v11, v5, s3, v4
	v_lshlrev_b32_e32 v4, 1, v16
	v_add3_u32 v3, 0, v3, v4
	ds_write_b128 v3, v[8:11]
	s_waitcnt vmcnt(0)
	v_mov_b32_e32 v4, v204
	v_mov_b32_e32 v5, v205
	v_mov_b32_e32 v6, v206
	v_mov_b32_e32 v7, v207
	v_mov_b32_e32 v8, v208
	v_mov_b32_e32 v9, v209
	v_mov_b32_e32 v10, v210
	v_mov_b32_e32 v11, v211
	v_bfe_u32 v12, v8, 16, 1
	v_add3_u32 v8, v8, v12, s84
	v_bfe_u32 v12, v9, 16, 1
	v_lshrrev_b32_e32 v8, 16, v8
	v_add3_u32 v9, v9, v12, s84
	v_and_or_b32 v8, v9, s3, v8
	v_bfe_u32 v9, v10, 16, 1
	v_add3_u32 v9, v10, v9, s84
	v_bfe_u32 v10, v11, 16, 1
	v_lshrrev_b32_e32 v9, 16, v9
	v_add3_u32 v10, v11, v10, s84
	v_and_or_b32 v9, v10, s3, v9
	v_bfe_u32 v10, v4, 16, 1
	v_add3_u32 v4, v4, v10, s84
	v_bfe_u32 v10, v5, 16, 1
	v_lshrrev_b32_e32 v4, 16, v4
	v_add3_u32 v5, v5, v10, s84
	v_and_or_b32 v10, v5, s3, v4
	v_bfe_u32 v4, v6, 16, 1
	v_add3_u32 v4, v6, v4, s84
	v_bfe_u32 v5, v7, 16, 1
	v_lshrrev_b32_e32 v4, 16, v4
	v_add3_u32 v5, v7, v5, s84
	v_and_or_b32 v11, v5, s3, v4
	ds_write_b128 v3, v[8:11] offset:34816
	v_add_u32_e32 v3, 0x200, v2
	v_mov_b32_e32 v2, v3
	s_andn2_b64 exec, exec, s[40:41]
	s_cbranch_execnz .LBB0_127

; __device__ __forceinline__ float softplusf(float z) { return fmaxf(z, 0.f) + log1pf(expf(-fabsf(z))); }
; __device__ __forceinline__ void fox_cum(const float* FLOG, float bh, int b, int h, float* cum, int tid) {
;     const int lane = tid & 63, wave = tid >> 6;
;     float v[4];
; #pragma unroll
;     for (int i = 0; i < 4; ++i) { const float f = FLOG[((size_t)b * SEQ + tid * 4 + i) * 4 + h] + bh; v[i] = -softplusf(-f); }
.LBB0_214:
	s_ashr_i32 s0, s58, 4
	s_bfe_u32 s10, s58, 0x20002
	s_ashr_i32 s1, s0, 31
	s_lshl_b32 s4, s10, 2
	s_lshl_b64 s[44:45], s[0:1], 11
	v_lshlrev_b32_e32 v2, 2, v118
	v_ashrrev_i32_e32 v3, 31, v2
	s_add_u32 s0, s56, s4
	v_lshl_add_u64 v[4:5], s[44:45], 0, v[2:3]
	s_addc_u32 s1, s57, 0
	v_mov_b32_e32 v1, s4
	v_lshl_add_u64 v[4:5], v[4:5], 4, s[0:1]
	global_load_dword v1, v1, s[42:43]
	s_mov_b32 s0, 0xb2a5705f
	global_load_dword v3, v[4:5], off
	global_load_dword v210, v[4:5], off offset:16
	global_load_dword v211, v[4:5], off offset:32
	global_load_dword v212, v[4:5], off offset:48
	s_mov_b32 s4, 0x3f2aaaab
	s_mov_b32 s5, 0x3f317218
	s_mov_b32 s1, 0x7f800000
	s_mov_b32 s8, 0x33800000
	v_and_b32_e32 v6, 63, v118
	s_waitcnt vmcnt(0)
	v_add_f32_e32 v3, v1, v3
	v_mul_f32_e64 v8, |v3|, s18
	v_fma_f32 v9, |v3|, s18, -v8
	v_rndne_f32_e32 v10, v8
	v_fma_f32 v9, |v3|, s0, v9
	v_sub_f32_e32 v8, v8, v10
	v_add_f32_e32 v8, v8, v9
	v_exp_f32_e32 v8, v8
	v_cvt_i32_f32_e32 v9, v10
	v_cmp_ngt_f32_e64 vcc, |v3|, s31
	v_max_f32_e64 v7, -v3, 0
	v_ldexp_f32 v8, v8, v9
	v_cndmask_b32_e32 v8, 0, v8, vcc
	v_cmp_nlt_f32_e64 vcc, |v3|, s30
	s_nop 1
	v_cndmask_b32_e32 v3, v181, v8, vcc
	v_add_f32_e32 v10, 1.0, v3
	v_add_f32_e32 v8, -1.0, v10
	v_sub_f32_e32 v9, v8, v10
	v_add_f32_e32 v9, 1.0, v9
	v_sub_f32_e32 v8, v3, v8
	v_add_f32_e32 v11, v8, v9
	v_frexp_mant_f32_e32 v8, v10
	v_cmp_gt_f32_e32 vcc, s4, v8
	v_cvt_f64_f32_e32 v[8:9], v10
	v_frexp_exp_i32_f64_e32 v8, v[8:9]
	v_subbrev_co_u32_e32 v8, vcc, 0, v8, vcc
	v_sub_u32_e32 v9, 0, v8
	v_ldexp_f32 v10, v10, v9
	v_ldexp_f32 v9, v11, v9
	v_add_f32_e32 v11, -1.0, v10
	v_add_f32_e32 v12, 1.0, v11
	v_sub_f32_e32 v12, v10, v12
	v_add_f32_e32 v12, v9, v12
	v_add_f32_e32 v13, v11, v12
	v_sub_f32_e32 v11, v11, v13
	v_add_f32_e32 v11, v12, v11
	v_add_f32_e32 v12, 1.0, v10
	v_add_f32_e32 v14, -1.0, v12
	v_sub_f32_e32 v10, v10, v14
	v_add_f32_e32 v9, v9, v10
	v_add_f32_e32 v10, v12, v9
	v_sub_f32_e32 v12, v12, v10
	v_add_f32_e32 v9, v9, v12
	v_rcp_f32_e32 v12, v10
	v_cvt_f32_i32_e32 v8, v8
	v_cmp_neq_f32_e32 vcc, s1, v3
	v_mul_f32_e32 v14, v13, v12
	v_mul_f32_e32 v15, v10, v14
	v_fma_f32 v16, v14, v10, -v15
	v_fmac_f32_e32 v16, v14, v9
	v_add_f32_e32 v17, v15, v16
	v_sub_f32_e32 v18, v13, v17
	v_sub_f32_e32 v13, v13, v18
	v_sub_f32_e32 v15, v17, v15
	v_sub_f32_e32 v13, v13, v17
	v_add_f32_e32 v11, v11, v13
	v_sub_f32_e32 v13, v15, v16
	v_add_f32_e32 v11, v13, v11
	v_add_f32_e32 v13, v18, v11
	v_mul_f32_e32 v15, v12, v13
	v_mul_f32_e32 v16, v10, v15
	v_fma_f32 v10, v15, v10, -v16
	v_fmac_f32_e32 v10, v15, v9
	v_sub_f32_e32 v9, v18, v13
	v_add_f32_e32 v9, v11, v9
	v_add_f32_e32 v11, v16, v10
	v_sub_f32_e32 v17, v13, v11
	v_sub_f32_e32 v13, v13, v17
	v_sub_f32_e32 v16, v11, v16
	v_sub_f32_e32 v11, v13, v11
	v_add_f32_e32 v9, v9, v11
	v_sub_f32_e32 v10, v16, v10
	v_add_f32_e32 v9, v10, v9
	v_add_f32_e32 v10, v14, v15
	v_add_f32_e32 v9, v17, v9
	v_sub_f32_e32 v11, v10, v14
	v_mul_f32_e32 v9, v12, v9
	v_sub_f32_e32 v11, v15, v11
	v_add_f32_e32 v9, v11, v9
	v_mul_f32_e32 v14, 0x3f317218, v8
	v_add_f32_e32 v11, v10, v9
	v_fma_f32 v15, v8, s5, -v14
	v_mul_f32_e32 v12, v11, v11
	v_fmac_f32_e32 v15, 0xb102e308, v8
	v_sub_f32_e32 v8, v11, v10
	v_fmamk_f32 v13, v12, 0x3e9b6dac, v166
	v_sub_f32_e32 v8, v9, v8
	v_add_f32_e32 v9, v14, v15
	v_fmaak_f32 v13, v12, v13, 0x3f2aaada
	v_sub_f32_e32 v10, v9, v14
	v_ldexp_f32 v14, v11, 1
	v_mul_f32_e32 v11, v11, v12
	v_mul_f32_e32 v11, v11, v13
	v_add_f32_e32 v12, v14, v11
	v_sub_f32_e32 v13, v12, v14
	v_ldexp_f32 v8, v8, 1
	v_sub_f32_e32 v11, v11, v13
	v_add_f32_e32 v8, v8, v11
	v_add_f32_e32 v11, v12, v8
	v_sub_f32_e32 v12, v11, v12
	v_sub_f32_e32 v8, v8, v12
	v_add_f32_e32 v12, v9, v11
	v_sub_f32_e32 v13, v12, v9
	v_sub_f32_e32 v14, v12, v13
	v_sub_f32_e32 v10, v15, v10
	v_sub_f32_e32 v9, v9, v14
	v_sub_f32_e32 v11, v11, v13
	v_add_f32_e32 v9, v11, v9
	v_add_f32_e32 v11, v10, v8
	v_sub_f32_e32 v13, v11, v10
	v_sub_f32_e32 v14, v11, v13
	v_sub_f32_e32 v10, v10, v14
	v_sub_f32_e32 v8, v8, v13
	v_add_f32_e32 v9, v11, v9
	v_add_f32_e32 v8, v8, v10
	v_add_f32_e32 v10, v12, v9
	v_sub_f32_e32 v11, v10, v12
	v_sub_f32_e32 v9, v9, v11
	v_add_f32_e32 v8, v8, v9
	v_add_f32_e32 v8, v10, v8
	v_cndmask_b32_e32 v8, v181, v8, vcc
	v_cmp_lt_f32_e64 vcc, |v3|, s8
	s_nop 1
	v_cndmask_b32_e32 v3, v8, v3, vcc
	v_add_f32_e32 v3, v7, v3
	v_mov_b32_e32 v7, v210
	s_waitcnt vmcnt(0)
; __device__ __forceinline__ float softplusf(float z) { return fmaxf(z, 0.f) + log1pf(expf(-fabsf(z))); }
; __device__ __forceinline__ void fox_cum(const float* FLOG, float bh, int b, int h, float* cum, int tid) {
;     ...
;     float v[4];
; #pragma unroll
;     for (int i = 0; i < 4; ++i) { const float f = FLOG[((size_t)b * SEQ + tid * 4 + i) * 4 + h] + bh; v[i] = -softplusf(-f); }
;     v[1] += v[0]; v[2] += v[1]; v[3] += v[2];
	v_add_f32_e32 v7, v1, v7
	v_mul_f32_e64 v8, |v7|, s18
	v_fma_f32 v9, |v7|, s18, -v8
	v_rndne_f32_e32 v11, v8
	v_fma_f32 v9, |v7|, s0, v9
	v_sub_f32_e32 v8, v8, v11
	v_add_f32_e32 v8, v8, v9
	v_exp_f32_e32 v8, v8
	v_cvt_i32_f32_e32 v9, v11
	v_cmp_ngt_f32_e64 vcc, |v7|, s31
	v_max_f32_e64 v10, -v7, 0
	v_ldexp_f32 v8, v8, v9
	v_cndmask_b32_e32 v8, 0, v8, vcc
	v_cmp_nlt_f32_e64 vcc, |v7|, s30
	s_nop 1
	v_cndmask_b32_e32 v7, v181, v8, vcc
	v_add_f32_e32 v11, 1.0, v7
	v_add_f32_e32 v8, -1.0, v11
	v_sub_f32_e32 v9, v8, v11
	v_add_f32_e32 v9, 1.0, v9
	v_sub_f32_e32 v8, v7, v8
	v_add_f32_e32 v12, v8, v9
	v_frexp_mant_f32_e32 v8, v11
	v_cmp_gt_f32_e32 vcc, s4, v8
	v_cvt_f64_f32_e32 v[8:9], v11
	v_frexp_exp_i32_f64_e32 v8, v[8:9]
	v_subbrev_co_u32_e32 v8, vcc, 0, v8, vcc
	v_sub_u32_e32 v9, 0, v8
	v_ldexp_f32 v11, v11, v9
	v_ldexp_f32 v9, v12, v9
	v_add_f32_e32 v12, -1.0, v11
	v_add_f32_e32 v13, 1.0, v12
	v_sub_f32_e32 v13, v11, v13
	v_add_f32_e32 v13, v9, v13
	v_add_f32_e32 v14, v12, v13
	v_sub_f32_e32 v12, v12, v14
	v_add_f32_e32 v12, v13, v12
	v_add_f32_e32 v13, 1.0, v11
	v_add_f32_e32 v15, -1.0, v13
	v_sub_f32_e32 v11, v11, v15
	v_add_f32_e32 v9, v9, v11
	v_add_f32_e32 v11, v13, v9
	v_sub_f32_e32 v13, v13, v11
	v_add_f32_e32 v9, v9, v13
	v_rcp_f32_e32 v13, v11
	v_cvt_f32_i32_e32 v8, v8
	v_cmp_neq_f32_e32 vcc, s1, v7
	v_mul_f32_e32 v15, v14, v13
	v_mul_f32_e32 v16, v11, v15
	v_fma_f32 v17, v15, v11, -v16
	v_fmac_f32_e32 v17, v15, v9
	v_add_f32_e32 v18, v16, v17
	v_sub_f32_e32 v19, v14, v18
	v_sub_f32_e32 v14, v14, v19
	v_sub_f32_e32 v16, v18, v16
	v_sub_f32_e32 v14, v14, v18
	v_add_f32_e32 v12, v12, v14
	v_sub_f32_e32 v14, v16, v17
	v_add_f32_e32 v12, v14, v12
	v_add_f32_e32 v14, v19, v12
	v_mul_f32_e32 v16, v13, v14
	v_mul_f32_e32 v17, v11, v16
	v_fma_f32 v11, v16, v11, -v17
	v_fmac_f32_e32 v11, v16, v9
	v_sub_f32_e32 v9, v19, v14
	v_add_f32_e32 v9, v12, v9
	v_add_f32_e32 v12, v17, v11
	v_sub_f32_e32 v18, v14, v12
	v_sub_f32_e32 v14, v14, v18
	v_sub_f32_e32 v17, v12, v17
	v_sub_f32_e32 v12, v14, v12
	v_add_f32_e32 v9, v9, v12
	v_sub_f32_e32 v11, v17, v11
	v_add_f32_e32 v9, v11, v9
	v_add_f32_e32 v11, v15, v16
	v_add_f32_e32 v9, v18, v9
	v_sub_f32_e32 v12, v11, v15
	v_mul_f32_e32 v9, v13, v9
	v_sub_f32_e32 v12, v16, v12
	v_add_f32_e32 v9, v12, v9
	v_mul_f32_e32 v15, 0x3f317218, v8
	v_add_f32_e32 v12, v11, v9
	v_fma_f32 v16, v8, s5, -v15
	v_mul_f32_e32 v13, v12, v12
	v_fmac_f32_e32 v16, 0xb102e308, v8
	v_sub_f32_e32 v8, v12, v11
	v_fmamk_f32 v14, v13, 0x3e9b6dac, v166
	v_sub_f32_e32 v8, v9, v8
	v_add_f32_e32 v9, v15, v16
	v_fmaak_f32 v14, v13, v14, 0x3f2aaada
	v_sub_f32_e32 v11, v9, v15
	v_ldexp_f32 v15, v12, 1
	v_mul_f32_e32 v12, v12, v13
	v_mul_f32_e32 v12, v12, v14
	v_add_f32_e32 v13, v15, v12
	v_sub_f32_e32 v14, v13, v15
	v_ldexp_f32 v8, v8, 1
	v_sub_f32_e32 v12, v12, v14
	v_add_f32_e32 v8, v8, v12
	v_add_f32_e32 v12, v13, v8
	v_sub_f32_e32 v13, v12, v13
	v_sub_f32_e32 v8, v8, v13
	v_add_f32_e32 v13, v9, v12
	v_sub_f32_e32 v14, v13, v9
	v_sub_f32_e32 v15, v13, v14
	v_sub_f32_e32 v11, v16, v11
	v_sub_f32_e32 v9, v9, v15
	v_sub_f32_e32 v12, v12, v14
	v_add_f32_e32 v9, v12, v9
	v_add_f32_e32 v12, v11, v8
	v_sub_f32_e32 v14, v12, v11
	v_sub_f32_e32 v15, v12, v14
	v_sub_f32_e32 v11, v11, v15
	v_sub_f32_e32 v8, v8, v14
	v_add_f32_e32 v9, v12, v9
	v_add_f32_e32 v8, v8, v11
	v_add_f32_e32 v11, v13, v9
	v_sub_f32_e32 v12, v11, v13
	v_sub_f32_e32 v9, v9, v12
	v_add_f32_e32 v8, v8, v9
	v_add_f32_e32 v8, v11, v8
	v_cndmask_b32_e32 v8, v181, v8, vcc
	v_cmp_lt_f32_e64 vcc, |v7|, s8
	s_nop 1
	v_cndmask_b32_e32 v7, v8, v7, vcc
	v_mov_b32_e32 v8, v211
	v_add_f32_e32 v7, v10, v7
	v_mov_b32_e32 v4, v212
	s_barrier
	s_waitcnt vmcnt(1)
	v_add_f32_e32 v8, v1, v8
	v_mul_f32_e64 v9, |v8|, s18
	v_fma_f32 v11, |v8|, s18, -v9
	v_rndne_f32_e32 v12, v9
	v_fma_f32 v11, |v8|, s0, v11
	v_sub_f32_e32 v9, v9, v12
	v_add_f32_e32 v9, v9, v11
	v_exp_f32_e32 v9, v9
	v_cvt_i32_f32_e32 v11, v12
	v_cmp_ngt_f32_e64 vcc, |v8|, s31
	v_max_f32_e64 v10, -v8, 0
	s_waitcnt vmcnt(0)
	v_add_f32_e32 v1, v1, v4
	v_ldexp_f32 v9, v9, v11
	v_cndmask_b32_e32 v9, 0, v9, vcc
	v_cmp_nlt_f32_e64 vcc, |v8|, s30
	v_mul_f32_e64 v4, |v1|, s18
	v_fma_f32 v5, |v1|, s18, -v4
	v_cndmask_b32_e32 v11, v181, v9, vcc
	v_add_f32_e32 v12, 1.0, v11
	v_add_f32_e32 v8, -1.0, v12
	v_sub_f32_e32 v9, v8, v12
	v_add_f32_e32 v9, 1.0, v9
	v_sub_f32_e32 v8, v11, v8
	v_add_f32_e32 v13, v8, v9
	v_frexp_mant_f32_e32 v8, v12
	v_cmp_gt_f32_e32 vcc, s4, v8
	v_cvt_f64_f32_e32 v[8:9], v12
	v_frexp_exp_i32_f64_e32 v8, v[8:9]
	v_subbrev_co_u32_e32 v8, vcc, 0, v8, vcc
	v_sub_u32_e32 v9, 0, v8
	v_ldexp_f32 v12, v12, v9
	v_ldexp_f32 v9, v13, v9
	v_add_f32_e32 v13, -1.0, v12
	v_add_f32_e32 v14, 1.0, v13
	v_sub_f32_e32 v14, v12, v14
	v_add_f32_e32 v14, v9, v14
	v_add_f32_e32 v15, v13, v14
	v_sub_f32_e32 v13, v13, v15
	v_add_f32_e32 v13, v14, v13
	v_add_f32_e32 v14, 1.0, v12
	v_add_f32_e32 v16, -1.0, v14
	v_sub_f32_e32 v12, v12, v16
	v_add_f32_e32 v9, v9, v12
	v_add_f32_e32 v12, v14, v9
	v_sub_f32_e32 v14, v14, v12
	v_add_f32_e32 v9, v9, v14
	v_rcp_f32_e32 v14, v12
	v_cvt_f32_i32_e32 v8, v8
	v_cmp_neq_f32_e32 vcc, s1, v11
	v_fma_f32 v5, |v1|, s0, v5
	v_mul_f32_e32 v16, v15, v14
	v_mul_f32_e32 v17, v12, v16
	v_fma_f32 v18, v16, v12, -v17
	v_fmac_f32_e32 v18, v16, v9
	v_add_f32_e32 v19, v17, v18
	v_sub_f32_e32 v20, v15, v19
	v_sub_f32_e32 v15, v15, v20
	v_sub_f32_e32 v17, v19, v17
	v_sub_f32_e32 v15, v15, v19
	v_add_f32_e32 v13, v13, v15
	v_sub_f32_e32 v15, v17, v18
	v_add_f32_e32 v13, v15, v13
	v_add_f32_e32 v15, v20, v13
	v_mul_f32_e32 v17, v14, v15
	v_mul_f32_e32 v18, v12, v17
	v_fma_f32 v12, v17, v12, -v18
	v_fmac_f32_e32 v12, v17, v9
; __device__ __forceinline__ float softplusf(float z) { return fmaxf(z, 0.f) + log1pf(expf(-fabsf(z))); }
; __device__ __forceinline__ void fox_cum(const float* FLOG, float bh, int b, int h, float* cum, int tid) {
;     ...
;     float v[4];
; #pragma unroll
;     for (int i = 0; i < 4; ++i) { const float f = FLOG[((size_t)b * SEQ + tid * 4 + i) * 4 + h] + bh; v[i] = -softplusf(-f); }
;     v[1] += v[0]; v[2] += v[1]; v[3] += v[2];
;     float incl = v[3];
; #pragma unroll
;     for (int o = 1; o < 64; o <<= 1) { const float up = __shfl_up(incl, o); if (lane >= o) incl += up; }
;     __syncthreads();
;     if (lane == 63) cum[2048 - 8 + wave] = incl;
;     __syncthreads();
	v_sub_f32_e32 v9, v20, v15
	v_add_f32_e32 v9, v13, v9
	v_add_f32_e32 v13, v18, v12
	v_sub_f32_e32 v19, v15, v13
	v_sub_f32_e32 v15, v15, v19
	v_sub_f32_e32 v18, v13, v18
	v_sub_f32_e32 v13, v15, v13
	v_add_f32_e32 v9, v9, v13
	v_sub_f32_e32 v12, v18, v12
	v_add_f32_e32 v9, v12, v9
	v_add_f32_e32 v12, v16, v17
	v_add_f32_e32 v9, v19, v9
	v_sub_f32_e32 v13, v12, v16
	v_mul_f32_e32 v9, v14, v9
	v_sub_f32_e32 v13, v17, v13
	v_add_f32_e32 v9, v13, v9
	v_mul_f32_e32 v16, 0x3f317218, v8
	v_add_f32_e32 v13, v12, v9
	v_fma_f32 v17, v8, s5, -v16
	v_mul_f32_e32 v14, v13, v13
	v_fmac_f32_e32 v17, 0xb102e308, v8
	v_sub_f32_e32 v8, v13, v12
	v_fmamk_f32 v15, v14, 0x3e9b6dac, v166
	v_sub_f32_e32 v8, v9, v8
	v_add_f32_e32 v9, v16, v17
	v_fmaak_f32 v15, v14, v15, 0x3f2aaada
	v_sub_f32_e32 v12, v9, v16
	v_ldexp_f32 v16, v13, 1
	v_mul_f32_e32 v13, v13, v14
	v_mul_f32_e32 v13, v13, v15
	v_add_f32_e32 v14, v16, v13
	v_sub_f32_e32 v15, v14, v16
	v_ldexp_f32 v8, v8, 1
	v_sub_f32_e32 v13, v13, v15
	v_add_f32_e32 v8, v8, v13
	v_add_f32_e32 v13, v14, v8
	v_sub_f32_e32 v14, v13, v14
	v_sub_f32_e32 v8, v8, v14
	v_add_f32_e32 v14, v9, v13
	v_sub_f32_e32 v15, v14, v9
	v_sub_f32_e32 v16, v14, v15
	v_sub_f32_e32 v12, v17, v12
	v_sub_f32_e32 v9, v9, v16
	v_sub_f32_e32 v13, v13, v15
	v_add_f32_e32 v9, v13, v9
	v_add_f32_e32 v13, v12, v8
	v_sub_f32_e32 v15, v13, v12
	v_sub_f32_e32 v16, v13, v15
	v_sub_f32_e32 v12, v12, v16
	v_sub_f32_e32 v8, v8, v15
	v_add_f32_e32 v9, v13, v9
	v_add_f32_e32 v8, v8, v12
	v_add_f32_e32 v12, v14, v9
	v_sub_f32_e32 v13, v12, v14
	v_sub_f32_e32 v9, v9, v13
	v_add_f32_e32 v8, v8, v9
	v_add_f32_e32 v8, v12, v8
	v_cndmask_b32_e32 v8, v181, v8, vcc
	v_cmp_lt_f32_e64 vcc, |v11|, s8
	v_max_f32_e64 v9, -v1, 0
	s_nop 0
	v_cndmask_b32_e32 v8, v8, v11, vcc
	v_add_f32_e32 v8, v10, v8
	v_rndne_f32_e32 v10, v4
	v_sub_f32_e32 v4, v4, v10
	v_add_f32_e32 v4, v4, v5
	v_exp_f32_e32 v4, v4
	v_cvt_i32_f32_e32 v5, v10
	v_cmp_ngt_f32_e64 vcc, |v1|, s31
	v_ldexp_f32 v4, v4, v5
	s_nop 0
	v_cndmask_b32_e32 v4, 0, v4, vcc
	v_cmp_nlt_f32_e64 vcc, |v1|, s30
	s_nop 1
	v_cndmask_b32_e32 v1, v181, v4, vcc
	v_add_f32_e32 v10, 1.0, v1
	v_add_f32_e32 v4, -1.0, v10
	v_sub_f32_e32 v5, v4, v10
	v_add_f32_e32 v5, 1.0, v5
	v_sub_f32_e32 v4, v1, v4
	v_add_f32_e32 v11, v4, v5
	v_frexp_mant_f32_e32 v4, v10
	v_cmp_gt_f32_e32 vcc, s4, v4
	v_cvt_f64_f32_e32 v[4:5], v10
	v_frexp_exp_i32_f64_e32 v4, v[4:5]
	v_subbrev_co_u32_e32 v4, vcc, 0, v4, vcc
	v_sub_u32_e32 v5, 0, v4
	v_ldexp_f32 v10, v10, v5
	v_ldexp_f32 v5, v11, v5
	v_add_f32_e32 v11, -1.0, v10
	v_add_f32_e32 v12, 1.0, v11
	v_sub_f32_e32 v12, v10, v12
	v_add_f32_e32 v12, v5, v12
	v_add_f32_e32 v13, v11, v12
	v_sub_f32_e32 v11, v11, v13
	v_add_f32_e32 v11, v12, v11
	v_add_f32_e32 v12, 1.0, v10
	v_add_f32_e32 v14, -1.0, v12
	v_sub_f32_e32 v10, v10, v14
	v_add_f32_e32 v5, v5, v10
	v_add_f32_e32 v10, v12, v5
	v_sub_f32_e32 v12, v12, v10
	v_add_f32_e32 v5, v5, v12
	v_rcp_f32_e32 v12, v10
	v_cvt_f32_i32_e32 v4, v4
	v_cmp_neq_f32_e32 vcc, s1, v1
	v_mul_f32_e32 v14, v13, v12
	v_mul_f32_e32 v15, v10, v14
	v_fma_f32 v16, v14, v10, -v15
	v_fmac_f32_e32 v16, v14, v5
	v_add_f32_e32 v17, v15, v16
	v_sub_f32_e32 v18, v13, v17
	v_sub_f32_e32 v13, v13, v18
	v_sub_f32_e32 v15, v17, v15
	v_sub_f32_e32 v13, v13, v17
	v_add_f32_e32 v11, v11, v13
	v_sub_f32_e32 v13, v15, v16
	v_add_f32_e32 v11, v13, v11
	v_add_f32_e32 v13, v18, v11
	v_mul_f32_e32 v15, v12, v13
	v_mul_f32_e32 v16, v10, v15
	v_fma_f32 v10, v15, v10, -v16
	v_fmac_f32_e32 v10, v15, v5
	v_sub_f32_e32 v5, v18, v13
	v_add_f32_e32 v5, v11, v5
	v_add_f32_e32 v11, v16, v10
	v_sub_f32_e32 v17, v13, v11
	v_sub_f32_e32 v13, v13, v17
	v_sub_f32_e32 v16, v11, v16
	v_sub_f32_e32 v11, v13, v11
	v_add_f32_e32 v5, v5, v11
	v_sub_f32_e32 v10, v16, v10
	v_add_f32_e32 v5, v10, v5
	v_add_f32_e32 v10, v14, v15
	v_add_f32_e32 v5, v17, v5
	v_sub_f32_e32 v11, v10, v14
	v_mul_f32_e32 v5, v12, v5
	v_sub_f32_e32 v11, v15, v11
	v_add_f32_e32 v5, v11, v5
	v_mul_f32_e32 v14, 0x3f317218, v4
	v_add_f32_e32 v11, v10, v5
	v_fma_f32 v15, v4, s5, -v14
	v_mul_f32_e32 v12, v11, v11
	v_fmac_f32_e32 v15, 0xb102e308, v4
	v_sub_f32_e32 v4, v11, v10
	v_fmamk_f32 v13, v12, 0x3e9b6dac, v166
	v_sub_f32_e32 v4, v5, v4
	v_add_f32_e32 v5, v14, v15
	v_fmaak_f32 v13, v12, v13, 0x3f2aaada
	v_sub_f32_e32 v10, v5, v14
	v_ldexp_f32 v14, v11, 1
	v_mul_f32_e32 v11, v11, v12
	v_mul_f32_e32 v11, v11, v13
	v_add_f32_e32 v12, v14, v11
	v_sub_f32_e32 v13, v12, v14
	v_ldexp_f32 v4, v4, 1
	v_sub_f32_e32 v11, v11, v13
	v_add_f32_e32 v4, v4, v11
	v_add_f32_e32 v11, v12, v4
	v_sub_f32_e32 v12, v11, v12
	v_sub_f32_e32 v4, v4, v12
	v_add_f32_e32 v12, v5, v11
	v_sub_f32_e32 v13, v12, v5
	v_sub_f32_e32 v14, v12, v13
	v_sub_f32_e32 v10, v15, v10
	v_sub_f32_e32 v5, v5, v14
	v_sub_f32_e32 v11, v11, v13
	v_add_f32_e32 v5, v11, v5
	v_add_f32_e32 v11, v10, v4
	v_sub_f32_e32 v13, v11, v10
	v_sub_f32_e32 v14, v11, v13
	v_sub_f32_e32 v10, v10, v14
	v_sub_f32_e32 v4, v4, v13
	v_add_f32_e32 v5, v11, v5
	v_add_f32_e32 v4, v4, v10
	v_add_f32_e32 v10, v12, v5
	v_sub_f32_e32 v11, v10, v12
	v_sub_f32_e32 v5, v5, v11
	v_add_f32_e32 v4, v4, v5
	v_add_f32_e32 v4, v10, v4
	v_cndmask_b32_e32 v4, v181, v4, vcc
	v_cmp_lt_f32_e64 vcc, |v1|, s8
	s_nop 1
	v_cndmask_b32_e32 v1, v4, v1, vcc
	v_add_f32_e32 v5, v9, v1
	v_sub_f32_e64 v1, -v3, v7
	v_add_u32_e32 v7, -1, v167
	v_cmp_lt_i32_e32 vcc, v7, v172
	v_sub_f32_e32 v4, v1, v8
	v_sub_f32_e32 v5, v4, v5
	v_cndmask_b32_e32 v7, v7, v167, vcc
	v_lshlrev_b32_e32 v7, 2, v7
	ds_bpermute_b32 v7, v7, v5
	v_cmp_eq_u32_e32 vcc, 0, v6
	v_add_u32_e32 v8, -2, v167
	s_waitcnt lgkmcnt(0)
	v_add_f32_e32 v7, v5, v7
	v_cndmask_b32_e32 v7, v7, v5, vcc
	v_cmp_lt_i32_e32 vcc, v8, v172
	s_nop 1
	v_cndmask_b32_e32 v8, v8, v167, vcc
	v_lshlrev_b32_e32 v8, 2, v8
	ds_bpermute_b32 v8, v8, v7
	v_cmp_gt_u32_e32 vcc, 2, v6
	s_waitcnt lgkmcnt(0)
	v_add_f32_e32 v8, v7, v8
	v_cndmask_b32_e32 v7, v8, v7, vcc
	v_add_u32_e32 v8, -4, v167
	v_cmp_lt_i32_e32 vcc, v8, v172
	s_nop 1
	v_cndmask_b32_e32 v8, v8, v167, vcc
	v_lshlrev_b32_e32 v8, 2, v8
	ds_bpermute_b32 v8, v8, v7
	v_cmp_gt_u32_e32 vcc, 4, v6
	s_waitcnt lgkmcnt(0)
	v_add_f32_e32 v8, v7, v8
	v_cndmask_b32_e32 v7, v8, v7, vcc
	v_add_u32_e32 v8, -8, v167
	v_cmp_lt_i32_e32 vcc, v8, v172
	s_nop 1
	v_cndmask_b32_e32 v8, v8, v167, vcc
	v_lshlrev_b32_e32 v8, 2, v8
	ds_bpermute_b32 v8, v8, v7
	v_cmp_gt_u32_e32 vcc, 8, v6
	s_waitcnt lgkmcnt(0)
	v_add_f32_e32 v8, v7, v8
	v_cndmask_b32_e32 v7, v8, v7, vcc
	v_add_u32_e32 v8, -16, v167
	v_cmp_lt_i32_e32 vcc, v8, v172
	s_nop 1
	v_cndmask_b32_e32 v8, v8, v167, vcc
	v_lshlrev_b32_e32 v8, 2, v8
	ds_bpermute_b32 v8, v8, v7
	v_cmp_gt_u32_e32 vcc, 16, v6
	s_waitcnt lgkmcnt(0)
	v_add_f32_e32 v8, v7, v8
	v_cndmask_b32_e32 v8, v8, v7, vcc
	v_subrev_u32_e32 v7, 32, v167
	v_cmp_lt_i32_e32 vcc, v7, v172
	s_nop 1
	v_cndmask_b32_e32 v7, v7, v167, vcc
	v_lshlrev_b32_e32 v7, 2, v7
	ds_bpermute_b32 v7, v7, v8
	v_cmp_eq_u32_e32 vcc, 63, v6
	s_waitcnt lgkmcnt(0)
	v_add_f32_e32 v9, v8, v7
	v_ashrrev_i32_e32 v7, 6, v118
	s_and_saveexec_b64 s[4:5], vcc
	s_cbranch_execz .LBB0_216
; __device__ __forceinline__ void fox_cum(const float* FLOG, float bh, int b, int h, float* cum, int tid) {
;     ...
;     if (lane == 63) cum[2048 - 8 + wave] = incl;
	v_readlane_b32 s0, v250, 5
	s_nop 1
	v_lshl_add_u32 v10, v7, 2, s0
	ds_write_b32 v10, v9 offset:8160
